# cross-phase prefetch: MIX1 issues the attention phase's Q tile and first K/V chunk (in-projection data) under its depthwise-conv loop; the attention prologue copies them
# baseline (speedup 1.0000x reference)
_Z10fwd_kernel4Args:
	v_writelane_b32 v255, 0, 28
	v_writelane_b32 v255, 0, 23
	v_writelane_b32 v255, 0, 24
	s_load_dwordx4 s[68:71], s[0:1], 0xb0
	s_load_dwordx2 s[46:47], s[0:1], 0xc0
	s_add_u32 s4, s0, 0xc0
	s_addc_u32 s5, s1, 0
	v_and_b32_e32 v137, 0x3ff, v0
	v_writelane_b32 v254, s4, 0
	v_cmp_gt_u32_e32 vcc, 16, v137
	s_nop 0
	v_writelane_b32 v254, s5, 1
	s_and_saveexec_b64 s[6:7], vcc
	v_lshl_add_u32 v1, v137, 2, 0
	v_add_u32_e32 v1, 0x257c0, v1
	v_mov_b32_e32 v2, 0
	ds_write_b32 v1, v2
	s_or_b64 exec, exec, s[6:7]
	s_waitcnt lgkmcnt(0)
	s_barrier
	s_load_dwordx2 s[74:75], s[0:1], 0xa8
	s_cmp_lg_u32 s70, 0
	s_mov_b32 s8, 0
	s_cselect_b64 s[52:53], -1, 0
	s_cmp_eq_u32 s70, 0
	v_cmp_eq_u32_e32 vcc, 0, v137
	s_cbranch_scc1 .LBB0_7
	s_getreg_b32 s3, hwreg(HW_REG_XCC_ID, 0, 4)
	s_and_b32 s8, s3, 15
	s_and_saveexec_b64 s[10:11], vcc
	s_cbranch_execz .LBB0_6
	s_mov_b64 s[4:5], exec
	v_mbcnt_lo_u32_b32 v1, s4, 0
	v_mbcnt_hi_u32_b32 v1, s5, v1
	v_cmp_eq_u32_e32 vcc, 0, v1
	s_and_b64 s[6:7], exec, vcc
	s_mov_b64 exec, s[6:7]
	s_cbranch_execz .LBB0_6
	s_lshl_b32 s3, s8, 8
	s_bcnt1_i32_b64 s4, s[4:5]
	v_mov_b32_e32 v1, s3
	v_mov_b32_e32 v2, s4
	s_waitcnt lgkmcnt(0)
	s_and_b32 s3, s2, 7
	s_lshl_b32 s3, s3, 6
	s_add_i32 s3, s3, 0x3600
	v_mov_b32_e32 v3, s3
	s_lshl_b32 s4, 1, s8
	v_mov_b32_e32 v4, s4
	global_atomic_or v4, v3, v4, s[74:75] sc0
	s_waitcnt vmcnt(0)
	global_atomic_add v1, v2, s[74:75] offset:1024

.LBB0_35:
	v_readlane_b32 s72, v255, 28
	s_lshl_b32 s70, s96, 6
	s_add_i32 s70, s70, 1
	s_cmp_eq_u32 s72, s70
	s_cselect_b32 s72, 1, 0
	v_mov_b32_e32 v44, v164
	s_lshl_b32 s35, s96, 6
	v_readfirstlane_b32 s34, v44
	v_and_b32_e32 v45, 15, v44
	s_ashr_i32 s38, s34, 7
	s_lshr_b32 s16, s34, 1
	v_and_or_b32 v78, s16, 32, v45
	s_lshl_b32 s16, s38, 6
	s_ashr_i32 s17, s16, 31
	s_lshl_b64 s[92:93], s[16:17], 1
	s_add_u32 s16, s15, s92
	v_or_b32_e32 v186, s35, v78
	s_addc_u32 s17, s40, s93
	v_and_b32_e32 v18, 48, v44
	v_mov_b32_e32 v19, v163
	v_lshl_add_u64 v[20:21], s[16:17], 0, v[18:19]
	v_or_b32_e32 v182, 16, v186
	v_mad_i64_i32 v[22:23], s[16:17], v186, s76, v[20:21]
	v_mad_i64_i32 v[20:21], s[16:17], v182, s76, v[20:21]
	s_and_b32 s16, s96, 0x7f
	s_sub_i32 s17, 8, s16
	s_cmp_lt_u32 s16, 8
	s_cselect_b32 s23, s17, 0
	s_lshl_b32 s39, s23, 6
	s_add_i32 s16, s35, s39
	s_addk_i32 s16, 0xfe00
	s_cmp_lg_u32 s72, 0
	s_cbranch_scc1 .Lmy_pf_s0
	global_load_dwordx4 v[26:29], v[22:23], off
.Lmy_pf_s0:
	s_cmp_lg_u32 s72, 0
	s_cbranch_scc1 .Lmy_pf_s1
	global_load_dwordx4 v[30:33], v[22:23], off offset:64
.Lmy_pf_s1:
	v_add_u32_e32 v22, 0x200, v44
	s_mul_hi_i32 s17, s16, 0x1600
	s_mulk_i32 s16, 0x1600
	v_ashrrev_i32_e32 v79, 5, v22
	v_add_u32_e32 v22, 0x400, v44
	s_add_u32 s16, s15, s16
	v_lshlrev_b32_e32 v19, 3, v44
	v_ashrrev_i32_e32 v80, 5, v22
	v_add_u32_e32 v22, 0x600, v44
	s_addc_u32 s17, s40, s17
	s_cmp_lg_u32 s72, 0
	s_cbranch_scc1 .Lmy_pf_s2
	global_load_dwordx4 v[34:37], v[20:21], off
.Lmy_pf_s2:
	s_cmp_lg_u32 s72, 0
	s_cbranch_scc1 .Lmy_pf_s3
	global_load_dwordx4 v[38:41], v[20:21], off offset:64
.Lmy_pf_s3:
	v_and_b32_e32 v20, 0xf8, v19
	v_ashrrev_i32_e32 v81, 5, v22
	v_mov_b64_e32 v[22:23], s[16:17]
	v_mad_i64_i32 v[24:25], s[16:17], v81, s76, v[22:23]
	v_lshlrev_b32_e32 v42, 1, v20
	v_mov_b32_e32 v43, v163
	v_lshl_add_u64 v[24:25], v[24:25], 0, v[42:43]
	s_cmp_lg_u32 s72, 0
	s_cbranch_scc1 .Lmy_pf_s4
	global_load_dwordx4 v[62:65], v[24:25], off offset:1024
.Lmy_pf_s4:
	s_cmp_lg_u32 s72, 0
	s_cbranch_scc1 .Lmy_pf_s5
	global_load_dwordx4 v[46:49], v[24:25], off offset:512
.Lmy_pf_s5:
	v_mad_i64_i32 v[24:25], s[16:17], v80, s76, v[22:23]
	v_ashrrev_i32_e32 v21, 5, v44
	v_lshl_add_u64 v[24:25], v[24:25], 0, v[42:43]
	s_cmp_lg_u32 s72, 0
	s_cbranch_scc1 .Lmy_pf_s6
	global_load_dwordx4 v[66:69], v[24:25], off offset:1024
.Lmy_pf_s6:
	s_cmp_lg_u32 s72, 0
	s_cbranch_scc1 .Lmy_pf_s7
	global_load_dwordx4 v[50:53], v[24:25], off offset:512
.Lmy_pf_s7:
	v_mad_i64_i32 v[24:25], s[16:17], v79, s76, v[22:23]
	v_mad_i64_i32 v[22:23], s[16:17], v21, s76, v[22:23]
	v_lshl_add_u64 v[24:25], v[24:25], 0, v[42:43]
	v_lshl_add_u64 v[22:23], v[22:23], 0, v[42:43]
	s_cmp_lg_u32 s72, 0
	s_cbranch_scc1 .Lmy_pf_s8
	global_load_dwordx4 v[70:73], v[24:25], off offset:1024
.Lmy_pf_s8:
	s_cmp_lg_u32 s72, 0
	s_cbranch_scc1 .Lmy_pf_s9
	global_load_dwordx4 v[54:57], v[24:25], off offset:512
.Lmy_pf_s9:
	s_cmp_lg_u32 s72, 0
	s_cbranch_scc1 .Lmy_pf_s10
	global_load_dwordx4 v[74:77], v[22:23], off offset:1024
.Lmy_pf_s10:
	s_cmp_lg_u32 s72, 0
	s_cbranch_scc1 .Lmy_pf_s11
	global_load_dwordx4 v[58:61], v[22:23], off offset:512
.Lmy_pf_s11:
	v_lshlrev_b32_e32 v24, 2, v44
	s_movk_i32 s0, 0x80
	v_bitop3_b32 v239, v24, 64, v213 bitop3:0x6c
	v_bitop3_b32 v238, v24, s0, v213 bitop3:0x6c
	v_lshrrev_b32_e32 v24, 2, v44
	v_mad_i64_i32 v[188:189], s[16:17], v21, s76, 0
	v_mad_i64_i32 v[190:191], s[16:17], v79, s76, 0
	v_mad_i64_i32 v[192:193], s[16:17], v80, s76, 0
	v_mad_i64_i32 v[194:195], s[16:17], v81, s76, 0
	v_bfe_u32 v23, v44, 2, 2
	v_and_b32_e32 v240, 12, v24
	v_add_u32_e32 v22, 0, v42
	s_and_b32 s16, s34, 0xffffff80
	v_or_b32_e32 v23, v240, v23
	s_add_i32 s17, s16, 0
	v_mad_u64_u32 v[196:197], s[34:35], v21, s77, v[22:23]
	v_mad_u64_u32 v[198:199], s[34:35], v79, s77, v[22:23]
	v_mad_u64_u32 v[200:201], s[34:35], v80, s77, v[22:23]
	v_mad_u64_u32 v[202:203], s[34:35], v81, s77, v[22:23]
	v_mul_u32_u24_e32 v22, 0x210, v23
	v_and_b32_e32 v19, 24, v19
	s_mulk_i32 s38, 0x404
	v_add3_u32 v197, s17, v22, v19
	v_or_b32_e32 v19, 0x1d0, v78
	v_add_u32_e32 v18, s17, v18
	s_add_i32 s16, s38, 0
	v_mul_u32_u24_e32 v21, 0x210, v45
	v_sub_u32_e32 v19, v19, v240
	v_ashrrev_i32_e32 v187, 31, v186
	v_ashrrev_i32_e32 v183, 31, v182
	s_add_i32 s16, s16, 0x23000
	v_add_u32_e32 v199, 0xa400, v197
	v_subrev_u32_e32 v201, s39, v19
	s_add_i32 s17, s41, s39
	v_mov_b32_e32 v181, 0xf149f2ca
	v_lshlrev_b32_e32 v204, 1, v20
	v_add_u32_e32 v203, v18, v21
	v_mov_b32_e32 v175, 0xf149f2ca
	s_mov_b64 s[34:35], s[36:37]
	v_mov_b32_e32 v78, 0
	v_mov_b32_e32 v79, v236
	v_mov_b32_e32 v80, v236
	v_mov_b32_e32 v81, v236
	v_mov_b32_e32 v94, 0
	v_mov_b32_e32 v95, v236
	v_mov_b32_e32 v96, v236
	v_mov_b32_e32 v97, v236
	v_mov_b32_e32 v42, 0
	v_mov_b32_e32 v43, v236
	v_mov_b32_e32 v44, v236
	v_mov_b32_e32 v45, v236
	v_mov_b32_e32 v90, 0
	v_mov_b32_e32 v91, v236
	v_mov_b32_e32 v92, v236
	v_mov_b32_e32 v93, v236
	v_mov_b32_e32 v18, 0
	v_mov_b32_e32 v19, v236
	v_mov_b32_e32 v20, v236
	v_mov_b32_e32 v21, v236
	v_mov_b32_e32 v82, 0
	v_mov_b32_e32 v83, v236
	v_mov_b32_e32 v84, v236
	v_mov_b32_e32 v85, v236
	v_mov_b32_e32 v22, 0
	v_mov_b32_e32 v23, v236
	v_mov_b32_e32 v24, v236
	v_mov_b32_e32 v25, v236
	v_mov_b32_e32 v86, 0
	v_mov_b32_e32 v87, v236
	v_mov_b32_e32 v88, v236
	v_mov_b32_e32 v89, v236
	v_mov_b32_e32 v184, 0
	v_mov_b32_e32 v185, v236
	s_cmp_eq_u32 s72, 0
	s_cbranch_scc1 .Lmy_pf_nocopy
	v_mov_b32_e32 v26, v100
	v_mov_b32_e32 v27, v101
	v_mov_b32_e32 v28, v102
	v_mov_b32_e32 v29, v103
	v_mov_b32_e32 v30, v104
	v_mov_b32_e32 v31, v105
	v_mov_b32_e32 v32, v106
	v_mov_b32_e32 v33, v107
	v_mov_b32_e32 v34, v108
	v_mov_b32_e32 v35, v109
	v_mov_b32_e32 v36, v110
	v_mov_b32_e32 v37, v111
	v_mov_b32_e32 v38, v112
	v_mov_b32_e32 v39, v113
	v_mov_b32_e32 v40, v114
	v_mov_b32_e32 v41, v115
	v_mov_b32_e32 v46, v142
	v_mov_b32_e32 v47, v143
	v_mov_b32_e32 v48, v144
	v_mov_b32_e32 v49, v145
	v_mov_b32_e32 v50, v132
	v_mov_b32_e32 v51, v133
	v_mov_b32_e32 v52, v134
	v_mov_b32_e32 v53, v135
	v_mov_b32_e32 v54, v124
	v_mov_b32_e32 v55, v125
	v_mov_b32_e32 v56, v126
	v_mov_b32_e32 v57, v127
	v_mov_b32_e32 v58, v116
	v_mov_b32_e32 v59, v117
	v_mov_b32_e32 v60, v118
	v_mov_b32_e32 v61, v119
	v_mov_b32_e32 v62, v146
	v_mov_b32_e32 v63, v147
	v_mov_b32_e32 v64, v148
	v_mov_b32_e32 v65, v149
	v_mov_b32_e32 v66, v138
	v_mov_b32_e32 v67, v139
	v_mov_b32_e32 v68, v140
	v_mov_b32_e32 v69, v141
	v_mov_b32_e32 v70, v128
	v_mov_b32_e32 v71, v129
	v_mov_b32_e32 v72, v130
	v_mov_b32_e32 v73, v131
	v_mov_b32_e32 v74, v120
	v_mov_b32_e32 v75, v121
	v_mov_b32_e32 v76, v122
	v_mov_b32_e32 v77, v123
	s_mov_b32 s72, 0
	s_nop 3
	v_writelane_b32 v255, s72, 28
.Lmy_pf_nocopy:
	s_cmp_lg_u32 s88, 0
	s_cbranch_scc0 .Lsc_pr_sc
	s_mov_b32 s95, 0

.LBB0_442:
	s_or_b64 exec, exec, s[28:29]
	s_mov_b64 s[16:17], s[60:61]
	s_waitcnt lgkmcnt(0)
	s_barrier
	s_mul_i32 s25, s14, 0x7c00
	s_add_u32 s16, s16, s25
	s_mul_hi_i32 s25, s14, 0x7c00
	s_addc_u32 s17, s17, s25
	v_lshlrev_b32_sdwa v162, v226, v37 dst_sel:DWORD dst_unused:UNUSED_PAD src0_sel:DWORD src1_sel:BYTE_0
	v_lshl_add_u64 v[24:25], s[16:17], 0, v[162:163]
	v_add_co_u32_e32 v8, vcc, s1, v24
	s_movk_i32 s16, 0x2000
	s_nop 0
	v_addc_co_u32_e32 v9, vcc, 0, v25, vcc
	v_add_co_u32_e32 v12, vcc, s16, v24
	s_movk_i32 s16, 0x3000
	s_nop 0
	v_addc_co_u32_e32 v13, vcc, 0, v25, vcc
	v_add_co_u32_e32 v16, vcc, s16, v24
	s_movk_i32 s16, 0x4000
	s_nop 0
	v_addc_co_u32_e32 v17, vcc, 0, v25, vcc
	v_add_co_u32_e32 v20, vcc, s16, v24
	s_movk_i32 s16, 0x5000
	s_nop 0
	v_addc_co_u32_e32 v21, vcc, 0, v25, vcc
	v_add_co_u32_e32 v26, vcc, s16, v24
	s_movk_i32 s16, 0x6000
	s_nop 0
	v_addc_co_u32_e32 v27, vcc, 0, v25, vcc
	v_add_co_u32_e32 v28, vcc, s16, v24
	s_movk_i32 s16, 0x7000
	s_nop 0
	v_addc_co_u32_e32 v29, vcc, 0, v25, vcc
	flat_load_dword v0, v[24:25]
	flat_load_dword v1, v[24:25] offset:1024
	flat_load_dword v2, v[24:25] offset:2048
	flat_load_dword v3, v[24:25] offset:3072
	flat_load_dword v4, v[8:9]
	flat_load_dword v5, v[8:9] offset:1024
	flat_load_dword v6, v[8:9] offset:2048
	flat_load_dword v7, v[8:9] offset:3072
	s_nop 0
	flat_load_dword v8, v[12:13]
	flat_load_dword v9, v[12:13] offset:1024
	flat_load_dword v10, v[12:13] offset:2048
	flat_load_dword v11, v[12:13] offset:3072
	s_nop 0
	flat_load_dword v12, v[16:17]
	flat_load_dword v13, v[16:17] offset:1024
	flat_load_dword v14, v[16:17] offset:2048
	flat_load_dword v15, v[16:17] offset:3072
	s_nop 0
	flat_load_dword v16, v[20:21]
	flat_load_dword v17, v[20:21] offset:1024
	flat_load_dword v18, v[20:21] offset:2048
	flat_load_dword v19, v[20:21] offset:3072
	s_nop 0
	flat_load_dword v20, v[26:27]
	flat_load_dword v21, v[26:27] offset:1024
	flat_load_dword v22, v[26:27] offset:2048
	flat_load_dword v23, v[26:27] offset:3072
	v_add_co_u32_e32 v30, vcc, s16, v24
	v_or_b32_sdwa v34, v37, s20 dst_sel:DWORD dst_unused:UNUSED_PAD src0_sel:BYTE_0 src1_sel:DWORD
	s_nop 0
	v_addc_co_u32_e32 v31, vcc, 0, v25, vcc
	flat_load_dword v24, v[28:29]
	flat_load_dword v25, v[28:29] offset:1024
	flat_load_dword v26, v[28:29] offset:2048
	flat_load_dword v27, v[28:29] offset:3072
	s_nop 0
	flat_load_dword v28, v[30:31]
	flat_load_dword v29, v[30:31] offset:1024
	s_nop 0
	flat_load_dword v30, v[30:31] offset:2048
	s_mov_b64 s[16:17], s[62:63]
	v_ashrrev_i32_e32 v35, 31, v34
	v_readlane_b32 s0, v254, 47
	v_lshl_add_u64 v[34:35], v[34:35], 2, s[16:17]
	flat_load_dword v31, v[34:35]
	v_ashrrev_i32_e32 v34, 3, v37
	v_lshlrev_b32_sdwa v35, v212, v37 dst_sel:DWORD dst_unused:UNUSED_PAD src0_sel:DWORD src1_sel:BYTE_0
	v_lshrrev_b32_e32 v37, 5, v34
	v_lshl_or_b32 v34, v37, 15, v162
	v_lshl_or_b32 v35, v37, 14, v35
	s_add_i32 s17, 0, 0x2000
	s_mov_b32 s16, 0
	v_add_u32_e32 v34, s0, v34
	v_lshrrev_b32_e32 v150, 6, v137
	v_and_b32_e32 v151, 15, v137
	v_bfe_u32 v152, v137, 4, 2
	v_and_b32_e32 v153, 1, v150
	v_lshrrev_b32_e32 v150, 1, v150
	v_lshl_add_u32 v151, v153, 5, v151
	v_add_u32_e32 v151, s71, v151
	v_lshlrev_b32_e32 v150, 7, v150
	v_lshl_add_u32 v150, v152, 4, v150
	v_mov_b32_e32 v155, 0x1600
	v_mad_u32_u24 v156, v151, v155, v150
	v_add_u32_e32 v157, 0x16000, v156
	v_mov_b32_e32 v158, s71
	v_lshrrev_b32_e32 v159, 6, v158
	v_and_b32_e32 v159, 0x7f, v159
	v_sub_u32_e32 v160, 8, v159
	v_max_i32_e32 v160, 0, v160
	v_lshl_add_u32 v158, v160, 6, v158
	v_add_u32_e32 v158, 0xfffffe00, v158
	v_lshrrev_b32_e32 v159, 5, v137
	v_add_u32_e32 v158, v158, v159
	v_and_b32_e32 v159, 31, v137
	v_lshlrev_b32_e32 v159, 4, v159
	v_mad_u32_u24 v158, v158, v155, v159
	global_load_dwordx4 v[100:103], v156, s[44:45]
	global_load_dwordx4 v[104:107], v156, s[44:45] offset:64
	global_load_dwordx4 v[108:111], v157, s[44:45]
	global_load_dwordx4 v[112:115], v157, s[44:45] offset:64
	global_load_dwordx4 v[116:119], v158, s[44:45] offset:512
	global_load_dwordx4 v[120:123], v158, s[44:45] offset:1024
	v_add_u32_e32 v158, 0x16000, v158
	global_load_dwordx4 v[124:127], v158, s[44:45] offset:512
	global_load_dwordx4 v[128:131], v158, s[44:45] offset:1024
	v_add_u32_e32 v158, 0x16000, v158
	global_load_dwordx4 v[132:135], v158, s[44:45] offset:512
	global_load_dwordx4 v[138:141], v158, s[44:45] offset:1024
	v_add_u32_e32 v158, 0x16000, v158
	global_load_dwordx4 v[142:145], v158, s[44:45] offset:512
	global_load_dwordx4 v[146:149], v158, s[44:45] offset:1024
	s_add_i32 s100, s71, 1
	s_nop 3
	v_writelane_b32 v255, s100, 28
	v_add_u32_e32 v35, s17, v35
.LBB0_443:
	v_add_u32_e32 v37, s16, v35
	ds_read_u16 v38, v37
	ds_read_u16 v39, v37 offset:512
	ds_read_u16 v40, v37 offset:1024
	ds_read_u16 v41, v37 offset:1536
	ds_read_u16 v42, v37 offset:2048
	ds_read_u16 v43, v37 offset:2560
	ds_read_u16 v44, v37 offset:3072
	ds_read_u16 v45, v37 offset:3584
	s_waitcnt lgkmcnt(0)
	v_lshlrev_b32_e32 v38, 16, v38
	s_waitcnt vmcnt(12)
	v_fma_f32 v38, v0, v38, v31
	v_lshlrev_b32_e32 v39, 16, v39
	v_fmac_f32_e32 v38, v1, v39
	v_fma_f32 v39, v0, v39, v31
	v_lshlrev_b32_e32 v40, 16, v40
	v_fmac_f32_e32 v38, v2, v40
	v_fmac_f32_e32 v39, v1, v40
	v_fma_f32 v40, v0, v40, v31
	v_lshlrev_b32_e32 v41, 16, v41
	ds_read_u16 v46, v37 offset:4096
	v_fmac_f32_e32 v38, v3, v41
	v_fmac_f32_e32 v39, v2, v41
	v_fmac_f32_e32 v40, v1, v41
	v_fma_f32 v41, v0, v41, v31
	v_lshlrev_b32_e32 v42, 16, v42
	v_fmac_f32_e32 v38, v4, v42
	v_fmac_f32_e32 v39, v3, v42
	v_fmac_f32_e32 v40, v2, v42
	v_fmac_f32_e32 v41, v1, v42
	v_fma_f32 v42, v0, v42, v31
	v_lshlrev_b32_e32 v43, 16, v43
	v_fmac_f32_e32 v38, v5, v43
	v_fmac_f32_e32 v39, v4, v43
	v_fmac_f32_e32 v40, v3, v43
	v_fmac_f32_e32 v41, v2, v43
	v_fmac_f32_e32 v42, v1, v43
	v_fma_f32 v43, v0, v43, v31
	v_lshlrev_b32_e32 v44, 16, v44
	v_fmac_f32_e32 v38, v6, v44
	v_fmac_f32_e32 v39, v5, v44
	v_fmac_f32_e32 v40, v4, v44
	v_fmac_f32_e32 v41, v3, v44
	v_fmac_f32_e32 v42, v2, v44
	v_fmac_f32_e32 v43, v1, v44
	v_fma_f32 v44, v0, v44, v31
	v_lshlrev_b32_e32 v45, 16, v45
	v_fmac_f32_e32 v38, v7, v45
	v_fmac_f32_e32 v39, v6, v45
	v_fmac_f32_e32 v40, v5, v45
	v_fmac_f32_e32 v41, v4, v45
	v_fmac_f32_e32 v42, v3, v45
	v_fmac_f32_e32 v43, v2, v45
	v_fmac_f32_e32 v44, v1, v45
	v_fma_f32 v45, v0, v45, v31
	s_waitcnt lgkmcnt(0)
	v_lshlrev_b32_e32 v46, 16, v46
	v_fmac_f32_e32 v38, v8, v46
	v_fmac_f32_e32 v39, v7, v46
	v_fmac_f32_e32 v40, v6, v46
	v_fmac_f32_e32 v41, v5, v46
	v_fmac_f32_e32 v42, v4, v46
	v_fmac_f32_e32 v43, v3, v46
	v_fmac_f32_e32 v44, v2, v46
	v_fmac_f32_e32 v45, v1, v46
	ds_read_u16 v46, v37 offset:4608
	s_addk_i32 s16, 0x1000
	s_cmpk_lg_i32 s16, 0x4000
	s_waitcnt lgkmcnt(0)
	v_lshlrev_b32_e32 v46, 16, v46
	v_fmac_f32_e32 v38, v9, v46
	v_fmac_f32_e32 v39, v8, v46
	v_fmac_f32_e32 v40, v7, v46
	v_fmac_f32_e32 v41, v6, v46
	v_fmac_f32_e32 v42, v5, v46
	v_fmac_f32_e32 v43, v4, v46
	v_fmac_f32_e32 v44, v3, v46
	v_fmac_f32_e32 v45, v2, v46
	ds_read_u16 v46, v37 offset:5120
	s_waitcnt lgkmcnt(0)
	v_lshlrev_b32_e32 v46, 16, v46
	v_fmac_f32_e32 v38, v10, v46
	v_fmac_f32_e32 v39, v9, v46
	v_fmac_f32_e32 v40, v8, v46
	v_fmac_f32_e32 v41, v7, v46
	v_fmac_f32_e32 v42, v6, v46
	v_fmac_f32_e32 v43, v5, v46
	v_fmac_f32_e32 v44, v4, v46
	v_fmac_f32_e32 v45, v3, v46
	ds_read_u16 v46, v37 offset:5632
	s_waitcnt lgkmcnt(0)
	v_lshlrev_b32_e32 v46, 16, v46
	v_fmac_f32_e32 v38, v11, v46
	v_fmac_f32_e32 v39, v10, v46
	v_fmac_f32_e32 v40, v9, v46
	v_fmac_f32_e32 v41, v8, v46
	v_fmac_f32_e32 v42, v7, v46
	v_fmac_f32_e32 v43, v6, v46
	v_fmac_f32_e32 v44, v5, v46
	v_fmac_f32_e32 v45, v4, v46
	ds_read_u16 v46, v37 offset:6144
	s_waitcnt lgkmcnt(0)
	v_lshlrev_b32_e32 v46, 16, v46
	v_fmac_f32_e32 v38, v12, v46
	v_fmac_f32_e32 v39, v11, v46
	v_fmac_f32_e32 v40, v10, v46
	v_fmac_f32_e32 v41, v9, v46
	v_fmac_f32_e32 v42, v8, v46
	v_fmac_f32_e32 v43, v7, v46
	v_fmac_f32_e32 v44, v6, v46
	v_fmac_f32_e32 v45, v5, v46
	ds_read_u16 v46, v37 offset:6656
	s_waitcnt lgkmcnt(0)
	v_lshlrev_b32_e32 v46, 16, v46
	v_fmac_f32_e32 v38, v13, v46
	v_fmac_f32_e32 v39, v12, v46
	v_fmac_f32_e32 v40, v11, v46
	v_fmac_f32_e32 v41, v10, v46
	v_fmac_f32_e32 v42, v9, v46
	v_fmac_f32_e32 v43, v8, v46
	v_fmac_f32_e32 v44, v7, v46
	v_fmac_f32_e32 v45, v6, v46
	ds_read_u16 v46, v37 offset:7168
	s_waitcnt lgkmcnt(0)
	v_lshlrev_b32_e32 v46, 16, v46
	v_fmac_f32_e32 v38, v14, v46
	v_fmac_f32_e32 v39, v13, v46
	v_fmac_f32_e32 v40, v12, v46
	v_fmac_f32_e32 v41, v11, v46
	v_fmac_f32_e32 v42, v10, v46
	v_fmac_f32_e32 v43, v9, v46
	v_fmac_f32_e32 v44, v8, v46
	v_fmac_f32_e32 v45, v7, v46
	ds_read_u16 v46, v37 offset:7680
	s_waitcnt lgkmcnt(0)
	v_lshlrev_b32_e32 v46, 16, v46
	v_fmac_f32_e32 v38, v15, v46
	v_fmac_f32_e32 v39, v14, v46
	v_fmac_f32_e32 v40, v13, v46
	v_fmac_f32_e32 v41, v12, v46
	v_fmac_f32_e32 v42, v11, v46
	v_fmac_f32_e32 v43, v10, v46
	v_fmac_f32_e32 v44, v9, v46
	v_fmac_f32_e32 v45, v8, v46
	ds_read_u16 v46, v37 offset:8192
	s_waitcnt lgkmcnt(0)
	v_lshlrev_b32_e32 v46, 16, v46
	v_fmac_f32_e32 v38, v16, v46
	v_fmac_f32_e32 v39, v15, v46
	v_fmac_f32_e32 v40, v14, v46
	v_fmac_f32_e32 v41, v13, v46
	v_fmac_f32_e32 v42, v12, v46
	v_fmac_f32_e32 v43, v11, v46
	v_fmac_f32_e32 v44, v10, v46
	v_fmac_f32_e32 v45, v9, v46
	ds_read_u16 v46, v37 offset:8704
	s_waitcnt lgkmcnt(0)
	v_lshlrev_b32_e32 v46, 16, v46
	v_fmac_f32_e32 v38, v17, v46
	v_fmac_f32_e32 v39, v16, v46
	v_fmac_f32_e32 v40, v15, v46
	v_fmac_f32_e32 v41, v14, v46
	v_fmac_f32_e32 v42, v13, v46
	v_fmac_f32_e32 v43, v12, v46
	v_fmac_f32_e32 v44, v11, v46
	v_fmac_f32_e32 v45, v10, v46
	ds_read_u16 v46, v37 offset:9216
	s_waitcnt lgkmcnt(0)
	v_lshlrev_b32_e32 v46, 16, v46
	v_fmac_f32_e32 v38, v18, v46
	v_fmac_f32_e32 v39, v17, v46
	v_fmac_f32_e32 v40, v16, v46
	v_fmac_f32_e32 v41, v15, v46
	v_fmac_f32_e32 v42, v14, v46
	v_fmac_f32_e32 v43, v13, v46
	v_fmac_f32_e32 v44, v12, v46
	v_fmac_f32_e32 v45, v11, v46
	ds_read_u16 v46, v37 offset:9728
	s_waitcnt lgkmcnt(0)
	v_lshlrev_b32_e32 v46, 16, v46
	v_fmac_f32_e32 v38, v19, v46
	v_fmac_f32_e32 v39, v18, v46
	v_fmac_f32_e32 v40, v17, v46
	v_fmac_f32_e32 v41, v16, v46
	v_fmac_f32_e32 v42, v15, v46
	v_fmac_f32_e32 v43, v14, v46
	v_fmac_f32_e32 v44, v13, v46
	v_fmac_f32_e32 v45, v12, v46
	ds_read_u16 v46, v37 offset:10240
	s_waitcnt lgkmcnt(0)
	v_lshlrev_b32_e32 v46, 16, v46
	v_fmac_f32_e32 v38, v20, v46
	v_fmac_f32_e32 v39, v19, v46
	v_fmac_f32_e32 v40, v18, v46
	v_fmac_f32_e32 v41, v17, v46
	v_fmac_f32_e32 v42, v16, v46
	v_fmac_f32_e32 v43, v15, v46
	v_fmac_f32_e32 v44, v14, v46
	v_fmac_f32_e32 v45, v13, v46
	ds_read_u16 v46, v37 offset:10752
	s_waitcnt lgkmcnt(0)
	v_lshlrev_b32_e32 v46, 16, v46
	v_fmac_f32_e32 v38, v21, v46
	v_fmac_f32_e32 v39, v20, v46
	v_fmac_f32_e32 v40, v19, v46
	v_fmac_f32_e32 v41, v18, v46
	v_fmac_f32_e32 v42, v17, v46
	v_fmac_f32_e32 v43, v16, v46
	v_fmac_f32_e32 v44, v15, v46
	v_fmac_f32_e32 v45, v14, v46
	ds_read_u16 v46, v37 offset:11264
	s_waitcnt lgkmcnt(0)
	v_lshlrev_b32_e32 v46, 16, v46
	v_fmac_f32_e32 v38, v22, v46
	v_fmac_f32_e32 v39, v21, v46
	v_fmac_f32_e32 v40, v20, v46
	v_fmac_f32_e32 v41, v19, v46
	v_fmac_f32_e32 v42, v18, v46
	v_fmac_f32_e32 v43, v17, v46
	v_fmac_f32_e32 v44, v16, v46
	v_fmac_f32_e32 v45, v15, v46
	ds_read_u16 v46, v37 offset:11776
	s_waitcnt lgkmcnt(0)
	v_lshlrev_b32_e32 v46, 16, v46
	v_fmac_f32_e32 v38, v23, v46
	v_fmac_f32_e32 v39, v22, v46
	v_fmac_f32_e32 v40, v21, v46
	v_fmac_f32_e32 v41, v20, v46
	v_fmac_f32_e32 v42, v19, v46
	v_fmac_f32_e32 v43, v18, v46
	v_fmac_f32_e32 v44, v17, v46
	v_fmac_f32_e32 v45, v16, v46
	ds_read_u16 v46, v37 offset:12288
	s_waitcnt lgkmcnt(0)
	v_lshlrev_b32_e32 v46, 16, v46
	v_fmac_f32_e32 v38, v24, v46
	v_fmac_f32_e32 v39, v23, v46
	v_fmac_f32_e32 v40, v22, v46
	v_fmac_f32_e32 v41, v21, v46
	v_fmac_f32_e32 v42, v20, v46
	v_fmac_f32_e32 v43, v19, v46
	v_fmac_f32_e32 v44, v18, v46
	v_fmac_f32_e32 v45, v17, v46
	ds_read_u16 v46, v37 offset:12800
	s_waitcnt lgkmcnt(0)
	v_lshlrev_b32_e32 v46, 16, v46
	v_fmac_f32_e32 v38, v25, v46
	v_fmac_f32_e32 v39, v24, v46
	v_fmac_f32_e32 v40, v23, v46
	v_fmac_f32_e32 v41, v22, v46
	v_fmac_f32_e32 v42, v21, v46
	v_fmac_f32_e32 v43, v20, v46
	v_fmac_f32_e32 v44, v19, v46
	v_fmac_f32_e32 v45, v18, v46
	ds_read_u16 v46, v37 offset:13312
	s_waitcnt lgkmcnt(0)
	v_lshlrev_b32_e32 v46, 16, v46
	v_fmac_f32_e32 v38, v26, v46
	v_fmac_f32_e32 v39, v25, v46
	v_fmac_f32_e32 v40, v24, v46
	v_fmac_f32_e32 v41, v23, v46
	v_fmac_f32_e32 v42, v22, v46
	v_fmac_f32_e32 v43, v21, v46
	v_fmac_f32_e32 v44, v20, v46
	v_fmac_f32_e32 v45, v19, v46
	ds_read_u16 v46, v37 offset:13824
	s_waitcnt lgkmcnt(0)
	v_lshlrev_b32_e32 v46, 16, v46
	v_fmac_f32_e32 v38, v27, v46
	v_fmac_f32_e32 v39, v26, v46
	v_fmac_f32_e32 v40, v25, v46
	v_fmac_f32_e32 v41, v24, v46
	v_fmac_f32_e32 v42, v23, v46
	v_fmac_f32_e32 v43, v22, v46
	v_fmac_f32_e32 v44, v21, v46
	v_fmac_f32_e32 v45, v20, v46
	ds_read_u16 v46, v37 offset:14336
	s_waitcnt lgkmcnt(0)
	v_lshlrev_b32_e32 v46, 16, v46
	v_fmac_f32_e32 v38, v28, v46
	v_fmac_f32_e32 v39, v27, v46
	v_fmac_f32_e32 v40, v26, v46
	v_fmac_f32_e32 v41, v25, v46
	v_fmac_f32_e32 v42, v24, v46
	v_fmac_f32_e32 v43, v23, v46
	v_fmac_f32_e32 v44, v22, v46
	v_fmac_f32_e32 v45, v21, v46
	ds_read_u16 v46, v37 offset:14848
	s_waitcnt lgkmcnt(0)
	v_lshlrev_b32_e32 v46, 16, v46
	v_fmac_f32_e32 v38, v29, v46
	v_fmac_f32_e32 v39, v28, v46
	v_fmac_f32_e32 v40, v27, v46
	v_fmac_f32_e32 v41, v26, v46
	v_fmac_f32_e32 v42, v25, v46
	v_fmac_f32_e32 v43, v24, v46
	v_fmac_f32_e32 v44, v23, v46
	v_fmac_f32_e32 v45, v22, v46
	ds_read_u16 v46, v37 offset:15360
	s_waitcnt lgkmcnt(0)
	v_lshlrev_b32_e32 v46, 16, v46
	v_fmac_f32_e32 v38, v30, v46
	v_fmac_f32_e32 v39, v29, v46
	v_fmac_f32_e32 v40, v28, v46
	v_fmac_f32_e32 v41, v27, v46
	v_fmac_f32_e32 v42, v26, v46
	v_fmac_f32_e32 v43, v25, v46
	v_fmac_f32_e32 v44, v24, v46
	v_fmac_f32_e32 v45, v23, v46
	ds_read_u16 v46, v37 offset:15872
	s_waitcnt lgkmcnt(0)
	v_lshlrev_b32_e32 v46, 16, v46
	v_fmac_f32_e32 v39, v30, v46
	v_fmac_f32_e32 v40, v29, v46
	v_fmac_f32_e32 v41, v28, v46
	v_fmac_f32_e32 v42, v27, v46
	v_fmac_f32_e32 v43, v26, v46
	v_fmac_f32_e32 v44, v25, v46
	v_fmac_f32_e32 v45, v24, v46
	ds_read_u16 v46, v37 offset:16384
	s_waitcnt lgkmcnt(0)
	v_lshlrev_b32_e32 v46, 16, v46
	v_fmac_f32_e32 v40, v30, v46
	v_fmac_f32_e32 v41, v29, v46
	v_fmac_f32_e32 v42, v28, v46
	v_fmac_f32_e32 v43, v27, v46
	v_fmac_f32_e32 v44, v26, v46
	v_fmac_f32_e32 v45, v25, v46
	ds_read_u16 v46, v37 offset:16896
	s_waitcnt lgkmcnt(0)
	v_lshlrev_b32_e32 v46, 16, v46
	v_fmac_f32_e32 v41, v30, v46
	v_fmac_f32_e32 v42, v29, v46
	v_fmac_f32_e32 v43, v28, v46
	v_fmac_f32_e32 v44, v27, v46
	v_fmac_f32_e32 v45, v26, v46
	ds_read_u16 v46, v37 offset:17408
	s_waitcnt lgkmcnt(0)
	v_lshlrev_b32_e32 v46, 16, v46
	v_fmac_f32_e32 v42, v30, v46
	v_fmac_f32_e32 v43, v29, v46
	v_fmac_f32_e32 v44, v28, v46
	v_fmac_f32_e32 v45, v27, v46
	ds_read_u16 v46, v37 offset:17920
	s_waitcnt lgkmcnt(0)
	v_lshlrev_b32_e32 v46, 16, v46
	v_fmac_f32_e32 v43, v30, v46
	v_fmac_f32_e32 v44, v29, v46
	v_fmac_f32_e32 v45, v28, v46
	ds_read_u16 v46, v37 offset:18432
	ds_read_u16 v37, v37 offset:18944
	s_waitcnt lgkmcnt(1)
	v_lshlrev_b32_e32 v46, 16, v46
	v_fmac_f32_e32 v45, v29, v46
	s_waitcnt lgkmcnt(0)
	v_lshlrev_b32_e32 v37, 16, v37
	v_fmac_f32_e32 v44, v30, v46
	v_fmac_f32_e32 v45, v30, v37
	ds_write2st64_b32 v34, v38, v39 offset1:4
	ds_write2st64_b32 v34, v40, v41 offset0:8 offset1:12
	ds_write2st64_b32 v34, v42, v43 offset0:16 offset1:20
	ds_write2st64_b32 v34, v44, v45 offset0:24 offset1:28
	v_add_u32_e32 v34, 0x2000, v34
	s_cbranch_scc1 .LBB0_443
	s_mov_b64 s[16:17], s[64:65]
	s_waitcnt lgkmcnt(0)
	s_barrier
	s_lshl_b64 s[26:27], s[20:21], 2
	s_add_u32 s16, s16, s26
	s_addc_u32 s17, s17, s27
	v_lshlrev_b32_e32 v162, 4, v32
	v_lshl_add_u64 v[0:1], s[16:17], 0, v[162:163]
	s_mov_b64 s[16:17], s[66:67]
	flat_load_dwordx4 v[0:3], v[0:1]
	s_add_u32 s16, s16, s26
	s_addc_u32 s17, s17, s27
	v_lshl_add_u64 v[4:5], s[16:17], 0, v[162:163]
	flat_load_dwordx4 v[4:7], v[4:5]
	s_lshl_b32 s17, s24, 13
	s_add_i32 s17, s17, 0
	s_lshl_b32 s16, s24, 3
	s_add_i32 s17, s17, 0xdc00
	v_xor_b32_e32 v10, 4, v36
	v_xor_b32_e32 v11, 8, v36
	v_xor_b32_e32 v12, 16, v36
	v_xor_b32_e32 v13, 32, v36
	v_xor_b32_e32 v14, 64, v36
	s_add_i32 s16, s71, s16
	v_add_u32_e32 v15, s17, v162
	s_mov_b32 s17, 0
	v_lshlrev_b32_e32 v162, 3, v32
	s_waitcnt vmcnt(0)
